# MLA inner loop rewritten by hand: staggered wave halves (2 barriers per tile), LDS fragment prefetch, 2-step-ahead global prefetch, packed f32 row sums
# speedup vs baseline: 1.0330x; 1.0330x over previous
; __device__ __forceinline__ void mla_unit(LAS unsigned char* lds, const bf16_t* Q, const bf16_t* K, const bf16_t* V, bf16_t* Y, const float* qgain, const float* ROPE, int b, int h, int qb) {
;     ...
;     if (wid >= 4) __builtin_amdgcn_s_setprio(1);
;     for (int t = 0; t < 64; t += 2) { MLA_STEP(p0, p1, n0, n1, t, ka1, kb1, vv0, ka0, kb0, vv1); MLA_STEP(n0, n1, p0, p1, t + 1, ka0, kb0, vv1, ka1, kb1, vv0); }
;     __builtin_amdgcn_s_setprio(0);
.LBB0_387:
	v_readfirstlane_b32 s10, v221
	s_nop 3
	s_cmp_lt_u32 s10, 0x100
	s_cbranch_scc0 .Lmla_noextra_bar
	s_barrier

; #define LAS __attribute__((address_space(3)))
; #define MFMA32(a, b, c) __builtin_amdgcn_mfma_f32_32x32x16_bf16((a), (b), (c), 0, 0, 0)
; __device__ __forceinline__ void mla_unit(LAS unsigned char* lds, const bf16_t* Q, const bf16_t* K, const bf16_t* V, bf16_t* Y, const float* qgain, const float* ROPE, int b, int h, int qb) {
;     ...
;     ka0 = *(const u32x4*)(kg0 + (size_t)128 * 96); if (has1) kb0 = *(const u32x4*)(kg1 + (size_t)128 * 96); vv1 = *(const u32x4*)(vg + (size_t)64 * 64);
;     __syncthreads();
;     f32x16 o0, o1, negm;
; #pragma unroll
;     for (int i = 0; i < 16; ++i) { o0[i] = 0.f; o1[i] = 0.f; negm[i] = 0.f; }
;     const int koff = r32 * KP + hi * 16;
;     const int voff = (4 * hi + ((lane & 15) >> 2)) * VP + (16 * ((lane >> 4) & 1) + 4 * (lane & 3)) * 2;
;     f32x16 p0, p1, n0, n1;
;     { const LAS unsigned char* kb_ = lds + MLA_K0 + koff; p0 = negm; p1 = negm;
; #pragma unroll
;       for (int d0 = 0; d0 < 6; ++d0) { const bf16x8 a0 = *(const LAS bf16x8*)(kb_ + d0 * 32), a1 = *(const LAS bf16x8*)(kb_ + 32 * KP + d0 * 32); p0 = MFMA32(a0, qf[d0], p0); p1 = MFMA32(a1, qf[d0], p1); } }
;     float m_ref, l_run = 0.f;
;     { const float mx = rowmax32(p0, p1); m_ref = mx;
; #pragma unroll
;       for (int i = 0; i < 16; ++i) { p0[i] -= mx; p1[i] -= mx; negm[i] = -mx; } }
;     ...
;     if (wid >= 4) __builtin_amdgcn_s_setprio(1);
.LBB0_398:
	s_or_b64 exec, exec, s[34:35]
	v_mul_u32_u24_e32 v0, 0xd0, v41
	v_add_co_u32_e32 v2, vcc, 0x2000, v34
	v_lshl_add_u32 v0, v220, 4, v0
	s_nop 0
	v_addc_co_u32_e32 v3, vcc, 0, v35, vcc
	v_add_u32_e32 v235, 0, v0
	global_load_dwordx4 v[142:145], v[2:3], off
	s_waitcnt lgkmcnt(0)
	s_barrier
	ds_read_b128 v[2:5], v235
	ds_read_b128 v[34:37], v235 offset:32
	s_waitcnt lgkmcnt(1)
	v_mfma_f32_32x32x16_bf16 v[18:33], v[2:5], v[114:117], 0
	ds_read_b128 v[2:5], v235 offset:6656
	s_cmp_lt_i32 s10, 4
	s_waitcnt lgkmcnt(1)
	v_mfma_f32_32x32x16_bf16 v[18:33], v[34:37], v[118:121], v[18:33]
	ds_read_b128 v[34:37], v235 offset:6688
	s_waitcnt lgkmcnt(1)
	v_mfma_f32_32x32x16_bf16 v[2:17], v[2:5], v[114:117], 0
	s_waitcnt lgkmcnt(0)
	v_mfma_f32_32x32x16_bf16 v[2:17], v[34:37], v[118:121], v[2:17]
	ds_read_b128 v[34:37], v235 offset:64
	s_waitcnt lgkmcnt(0)
	v_mfma_f32_32x32x16_bf16 v[18:33], v[34:37], v[122:125], v[18:33]
	ds_read_b128 v[34:37], v235 offset:6720
	s_waitcnt lgkmcnt(0)
	v_mfma_f32_32x32x16_bf16 v[2:17], v[34:37], v[122:125], v[2:17]
	ds_read_b128 v[34:37], v235 offset:96
	s_waitcnt lgkmcnt(0)
	v_mfma_f32_32x32x16_bf16 v[18:33], v[34:37], v[126:129], v[18:33]
	ds_read_b128 v[34:37], v235 offset:6752
	s_waitcnt lgkmcnt(0)
	v_mfma_f32_32x32x16_bf16 v[2:17], v[34:37], v[126:129], v[2:17]
	ds_read_b128 v[34:37], v235 offset:128
	s_waitcnt lgkmcnt(0)
	v_mfma_f32_32x32x16_bf16 v[18:33], v[34:37], v[130:133], v[18:33]
	ds_read_b128 v[34:37], v235 offset:6784
	s_waitcnt lgkmcnt(0)
	v_mfma_f32_32x32x16_bf16 v[2:17], v[34:37], v[130:133], v[2:17]
	ds_read_b128 v[34:37], v235 offset:160
	s_waitcnt lgkmcnt(0)
	v_mfma_f32_32x32x16_bf16 v[18:33], v[34:37], v[134:137], v[18:33]
	ds_read_b128 v[34:37], v235 offset:6816
	v_max3_f32 v0, v18, v19, v20
	s_nop 0
	v_max3_f32 v0, v0, v21, v22
	s_nop 0
	v_max3_f32 v0, v0, v23, v24
	s_waitcnt lgkmcnt(0)
	v_mfma_f32_32x32x16_bf16 v[2:17], v[34:37], v[134:137], v[2:17]
	v_max3_f32 v34, v2, v3, v4
	v_max3_f32 v0, v0, v25, v26
	s_nop 0
	v_max3_f32 v34, v34, v5, v6
	v_max3_f32 v0, v0, v27, v28
	s_nop 0
	v_max3_f32 v34, v34, v7, v8
	v_max3_f32 v0, v0, v29, v30
	s_nop 0
	v_max3_f32 v34, v34, v9, v10
	v_max3_f32 v0, v0, v31, v32
	s_nop 0
	v_max3_f32 v34, v34, v11, v12
	v_max3_f32 v0, v0, v33, v17
	s_nop 0
	v_max3_f32 v34, v34, v13, v14
	s_nop 0
	v_max3_f32 v34, v34, v15, v16
	s_nop 0
	v_max3_f32 v0, v0, v34, v34
	ds_bpermute_b32 v34, v222, v0
	s_waitcnt lgkmcnt(0)
	v_max3_f32 v237, v0, v34, v0
	s_cbranch_scc1 .LBB0_400
	s_barrier

.LBB0_402:
	v_readfirstlane_b32 s11, v221
	v_add_u32_e32 v212, 0x9000, v212
	v_add_u32_e32 v214, 0x9000, v214
	v_add_u32_e32 v210, 0x4000, v210
	s_cmp_lt_u32 s11, 0x100
	s_cselect_b32 s11, 1, 0
	s_cmp_eq_u32 s11, 1
	s_cbranch_scc1 .Lmla_glue_L
	global_load_dwordx4 v[106:109], v212, s[2:3]
	global_load_dwordx4 v[102:105], v210, s[6:7]
	v_add_u32_e32 v212, 0x3000, v212
	v_add_u32_e32 v210, 0x2000, v210
	s_branch .Lmla_loop_T
.Lmla_glue_L:
	global_load_dwordx4 v[106:109], v212, s[2:3]
	global_load_dwordx4 v[110:113], v214, s[2:3]
	global_load_dwordx4 v[102:105], v210, s[6:7]
	v_add_u32_e32 v212, 0x3000, v212
	v_add_u32_e32 v214, 0x3000, v214
	v_add_u32_e32 v210, 0x2000, v210
	s_branch .Lmla_loop_L
.Lmla_loop_T:
	s_waitcnt vmcnt(2)
	ds_write_b128 v223, v[138:141]
	ds_write_b128 v233, v[142:145] offset:38912
	ds_read_b128 v[146:149], v235 offset:13312
	ds_read_b128 v[150:153], v235 offset:13344
	ds_read_b128 v[154:157], v235 offset:13376
	ds_read_b128 v[158:161], v235 offset:13408
	ds_read_b128 v[162:165], v235 offset:13440
	ds_read_b128 v[166:169], v235 offset:13472
	ds_read_b64_tr_b16 v[82:83], v238 offset:26624
	ds_read_b64_tr_b16 v[84:85], v238 offset:28160
	ds_read_b64_tr_b16 v[86:87], v238 offset:26688
	ds_read_b64_tr_b16 v[88:89], v238 offset:28224
	ds_read_b64_tr_b16 v[90:91], v238 offset:29696
	ds_read_b64_tr_b16 v[92:93], v238 offset:31232
	ds_read_b64_tr_b16 v[94:95], v238 offset:29760
	ds_read_b64_tr_b16 v[96:97], v238 offset:31296
	ds_read_b64_tr_b16 v[194:195], v238 offset:32768
	ds_read_b64_tr_b16 v[196:197], v238 offset:34304
	ds_read_b64_tr_b16 v[198:199], v238 offset:32832
	ds_read_b64_tr_b16 v[200:201], v238 offset:34368
	ds_read_b64_tr_b16 v[202:203], v238 offset:35840
	ds_read_b64_tr_b16 v[204:205], v238 offset:37376
	ds_read_b64_tr_b16 v[240:241], v238 offset:35904
	ds_read_b64_tr_b16 v[242:243], v238 offset:37440
	ds_read_b128 v[170:173], v235 offset:19968
	ds_read_b128 v[174:177], v235 offset:20000
	ds_read_b128 v[178:181], v235 offset:20032
	ds_read_b128 v[182:185], v235 offset:20064
	ds_read_b128 v[186:189], v235 offset:20096
	ds_read_b128 v[190:193], v235 offset:20128
	global_load_dwordx4 v[138:141], v212, s[2:3]
	global_load_dwordx4 v[142:145], v210, s[6:7]
	v_add_u32_e32 v212, 0x3000, v212
	v_add_u32_e32 v210, 0x2000, v210
	v_max3_f32 v0, v66, v67, v68
	v_max3_f32 v216, v34, v35, v36
	v_max3_f32 v0, v0, v69, v70
	v_max3_f32 v216, v216, v37, v38
	v_max3_f32 v0, v0, v71, v72
	v_max3_f32 v216, v216, v39, v40
	v_max3_f32 v0, v0, v73, v74
	v_max3_f32 v216, v216, v41, v42
	v_max3_f32 v0, v0, v75, v76
	v_max3_f32 v216, v216, v43, v44
	v_max3_f32 v0, v0, v77, v78
	v_max3_f32 v216, v216, v45, v46
	v_max3_f32 v0, v0, v79, v80
	v_max3_f32 v216, v216, v47, v48
	v_max3_f32 v0, v0, v81, v49
	v_max_f32_e32 v0, v0, v216
	v_mov_b32_e32 v216, v0
	s_nop 1
	v_permlane32_swap_b32_e32 v0, v216
	v_max_f32_e32 v0, v0, v216
	v_cmp_lt_f32_e32 vcc, s52, v0
	s_cbranch_vccz .Lmla_aT_norescale
	v_max_f32_e32 v0, 0, v0
	v_exp_f32_e64 v217, -v0
	v_add_f32_e32 v237, v237, v0
	v_sub_f32_e32 v66, v66, v0
	v_sub_f32_e32 v34, v34, v0
	v_sub_f32_e32 v67, v67, v0
	v_sub_f32_e32 v35, v35, v0
	v_sub_f32_e32 v68, v68, v0
	v_sub_f32_e32 v36, v36, v0
	v_sub_f32_e32 v69, v69, v0
	v_sub_f32_e32 v37, v37, v0
	v_sub_f32_e32 v70, v70, v0
	v_sub_f32_e32 v38, v38, v0
	v_sub_f32_e32 v71, v71, v0
	v_sub_f32_e32 v39, v39, v0
	v_sub_f32_e32 v72, v72, v0
	v_sub_f32_e32 v40, v40, v0
	v_sub_f32_e32 v73, v73, v0
	v_sub_f32_e32 v41, v41, v0
	v_sub_f32_e32 v74, v74, v0
	v_sub_f32_e32 v42, v42, v0
	v_sub_f32_e32 v75, v75, v0
	v_sub_f32_e32 v43, v43, v0
	v_sub_f32_e32 v76, v76, v0
	v_sub_f32_e32 v44, v44, v0
	v_sub_f32_e32 v77, v77, v0
	v_sub_f32_e32 v45, v45, v0
	v_sub_f32_e32 v78, v78, v0
	v_sub_f32_e32 v46, v46, v0
	v_sub_f32_e32 v79, v79, v0
	v_sub_f32_e32 v47, v47, v0
	v_sub_f32_e32 v80, v80, v0
	v_sub_f32_e32 v48, v48, v0
	v_sub_f32_e32 v81, v81, v0
	v_sub_f32_e32 v49, v49, v0
	v_mul_f32_e32 v2, v2, v217
	v_mul_f32_e32 v3, v3, v217
	v_mul_f32_e32 v4, v4, v217
	v_mul_f32_e32 v5, v5, v217
	v_mul_f32_e32 v6, v6, v217
	v_mul_f32_e32 v7, v7, v217
	v_mul_f32_e32 v8, v8, v217
	v_mul_f32_e32 v9, v9, v217
	v_mul_f32_e32 v10, v10, v217
	v_mul_f32_e32 v11, v11, v217
	v_mul_f32_e32 v12, v12, v217
	v_mul_f32_e32 v13, v13, v217
	v_mul_f32_e32 v14, v14, v217
	v_mul_f32_e32 v15, v15, v217
	v_mul_f32_e32 v16, v16, v217
	v_mul_f32_e32 v17, v17, v217
	v_mul_f32_e32 v18, v18, v217
	v_mul_f32_e32 v19, v19, v217
	v_mul_f32_e32 v20, v20, v217
	v_mul_f32_e32 v21, v21, v217
	v_mul_f32_e32 v22, v22, v217
	v_mul_f32_e32 v23, v23, v217
	v_mul_f32_e32 v24, v24, v217
	v_mul_f32_e32 v25, v25, v217
	v_mul_f32_e32 v26, v26, v217
	v_mul_f32_e32 v27, v27, v217
	v_mul_f32_e32 v28, v28, v217
	v_mul_f32_e32 v29, v29, v217
	v_mul_f32_e32 v30, v30, v217
	v_mul_f32_e32 v31, v31, v217
	v_mul_f32_e32 v32, v32, v217
	v_mul_f32_e32 v33, v33, v217
	v_mul_f32_e32 v239, v239, v217
	v_xor_b32_e32 v50, 0x80000000, v237
	v_mov_b32_e32 v51, v50
	v_mov_b32_e32 v52, v50
	v_mov_b32_e32 v53, v50
	v_mov_b32_e32 v54, v50
	v_mov_b32_e32 v55, v50
	v_mov_b32_e32 v56, v50
	v_mov_b32_e32 v57, v50
	v_mov_b32_e32 v58, v50
	v_mov_b32_e32 v59, v50
	v_mov_b32_e32 v60, v50
	v_mov_b32_e32 v61, v50
	v_mov_b32_e32 v62, v50
	v_mov_b32_e32 v63, v50
	v_mov_b32_e32 v64, v50
	v_mov_b32_e32 v65, v50
.Lmla_aT_norescale:
	v_exp_f32_e32 v66, v66
	v_exp_f32_e32 v34, v34
	v_exp_f32_e32 v67, v67
	v_exp_f32_e32 v35, v35
	v_exp_f32_e32 v68, v68
	v_exp_f32_e32 v36, v36
	v_exp_f32_e32 v69, v69
	v_exp_f32_e32 v37, v37
	v_exp_f32_e32 v70, v70
	v_exp_f32_e32 v38, v38
	v_exp_f32_e32 v71, v71
	v_exp_f32_e32 v39, v39
	v_exp_f32_e32 v72, v72
	v_exp_f32_e32 v40, v40
	v_exp_f32_e32 v73, v73
	v_exp_f32_e32 v41, v41
	v_exp_f32_e32 v74, v74
	v_exp_f32_e32 v42, v42
	v_exp_f32_e32 v75, v75
	v_exp_f32_e32 v43, v43
	v_exp_f32_e32 v76, v76
	v_exp_f32_e32 v44, v44
	v_exp_f32_e32 v77, v77
	v_exp_f32_e32 v45, v45
	v_exp_f32_e32 v78, v78
	v_exp_f32_e32 v46, v46
	v_exp_f32_e32 v79, v79
	v_exp_f32_e32 v47, v47
	v_exp_f32_e32 v80, v80
	v_exp_f32_e32 v48, v48
	v_exp_f32_e32 v81, v81
	v_exp_f32_e32 v49, v49
	v_pk_add_f32 v[218:219], v[66:67], v[68:69]
	v_pk_add_f32 v[244:245], v[34:35], v[36:37]
	v_pk_add_f32 v[218:219], v[218:219], v[70:71]
	v_pk_add_f32 v[244:245], v[244:245], v[38:39]
	v_pk_add_f32 v[218:219], v[218:219], v[72:73]
	v_pk_add_f32 v[244:245], v[244:245], v[40:41]
	v_pk_add_f32 v[218:219], v[218:219], v[74:75]
	v_pk_add_f32 v[244:245], v[244:245], v[42:43]
	v_pk_add_f32 v[218:219], v[218:219], v[76:77]
	v_pk_add_f32 v[244:245], v[244:245], v[44:45]
	v_pk_add_f32 v[218:219], v[218:219], v[78:79]
	v_pk_add_f32 v[244:245], v[244:245], v[46:47]
	v_pk_add_f32 v[218:219], v[218:219], v[80:81]
	v_pk_add_f32 v[244:245], v[244:245], v[48:49]
	v_pk_add_f32 v[218:219], v[218:219], v[244:245]
	v_add_f32_e32 v218, v218, v219
	v_add_f32_e32 v239, v239, v218
	v_cvt_pk_bf16_f32 v66, v66, v67
	v_cvt_pk_bf16_f32 v67, v68, v69
	v_cvt_pk_bf16_f32 v68, v70, v71
	v_cvt_pk_bf16_f32 v69, v72, v73
	v_cvt_pk_bf16_f32 v70, v74, v75
	v_cvt_pk_bf16_f32 v71, v76, v77
	v_cvt_pk_bf16_f32 v72, v78, v79
	v_cvt_pk_bf16_f32 v73, v80, v81
	v_cvt_pk_bf16_f32 v74, v34, v35
	v_cvt_pk_bf16_f32 v75, v36, v37
	v_cvt_pk_bf16_f32 v76, v38, v39
	v_cvt_pk_bf16_f32 v77, v40, v41
	v_cvt_pk_bf16_f32 v78, v42, v43
	v_cvt_pk_bf16_f32 v79, v44, v45
	v_cvt_pk_bf16_f32 v80, v46, v47
	v_cvt_pk_bf16_f32 v81, v48, v49
	s_waitcnt lgkmcnt(0)
	s_barrier
	v_mfma_f32_32x32x16_bf16 v[34:49], v[146:149], v[114:117], v[50:65]
	v_mfma_f32_32x32x16_bf16 v[34:49], v[150:153], v[118:121], v[34:49]
	v_mfma_f32_32x32x16_bf16 v[34:49], v[154:157], v[122:125], v[34:49]
	v_mfma_f32_32x32x16_bf16 v[34:49], v[158:161], v[126:129], v[34:49]
	v_mfma_f32_32x32x16_bf16 v[34:49], v[162:165], v[130:133], v[34:49]
	v_mfma_f32_32x32x16_bf16 v[34:49], v[166:169], v[134:137], v[34:49]
	v_mfma_f32_32x32x16_bf16 v[18:33], v[82:85], v[66:69], v[18:33]
	v_mfma_f32_32x32x16_bf16 v[2:17], v[86:89], v[66:69], v[2:17]
	v_mfma_f32_32x32x16_bf16 v[18:33], v[90:93], v[70:73], v[18:33]
	v_mfma_f32_32x32x16_bf16 v[2:17], v[94:97], v[70:73], v[2:17]
	v_mfma_f32_32x32x16_bf16 v[18:33], v[194:197], v[74:77], v[18:33]
	v_mfma_f32_32x32x16_bf16 v[2:17], v[198:201], v[74:77], v[2:17]
	v_mfma_f32_32x32x16_bf16 v[18:33], v[202:205], v[78:81], v[18:33]
	v_mfma_f32_32x32x16_bf16 v[2:17], v[240:243], v[78:81], v[2:17]
	v_mfma_f32_32x32x16_bf16 v[66:81], v[170:173], v[114:117], v[50:65]
	v_mfma_f32_32x32x16_bf16 v[66:81], v[174:177], v[118:121], v[66:81]
	v_mfma_f32_32x32x16_bf16 v[66:81], v[178:181], v[122:125], v[66:81]
	v_mfma_f32_32x32x16_bf16 v[66:81], v[182:185], v[126:129], v[66:81]
	v_mfma_f32_32x32x16_bf16 v[66:81], v[186:189], v[130:133], v[66:81]
	v_mfma_f32_32x32x16_bf16 v[66:81], v[190:193], v[134:137], v[66:81]
	s_waitcnt lgkmcnt(0)
	s_barrier
	s_waitcnt vmcnt(2)
	ds_write_b128 v223, v[106:109] offset:13312
	ds_write_b128 v233, v[102:105] offset:26624
	ds_read_b128 v[146:149], v235 offset:0
	ds_read_b128 v[150:153], v235 offset:32
	ds_read_b128 v[154:157], v235 offset:64
	ds_read_b128 v[158:161], v235 offset:96
	ds_read_b128 v[162:165], v235 offset:128
	ds_read_b128 v[166:169], v235 offset:160
	ds_read_b64_tr_b16 v[82:83], v238 offset:38912
	ds_read_b64_tr_b16 v[84:85], v238 offset:40448
	ds_read_b64_tr_b16 v[86:87], v238 offset:38976
	ds_read_b64_tr_b16 v[88:89], v238 offset:40512
	ds_read_b64_tr_b16 v[90:91], v238 offset:41984
	ds_read_b64_tr_b16 v[92:93], v238 offset:43520
	ds_read_b64_tr_b16 v[94:95], v238 offset:42048
	ds_read_b64_tr_b16 v[96:97], v238 offset:43584
	ds_read_b64_tr_b16 v[194:195], v238 offset:45056
	ds_read_b64_tr_b16 v[196:197], v238 offset:46592
	ds_read_b64_tr_b16 v[198:199], v238 offset:45120
	ds_read_b64_tr_b16 v[200:201], v238 offset:46656
	ds_read_b64_tr_b16 v[202:203], v238 offset:48128
	ds_read_b64_tr_b16 v[204:205], v238 offset:49664
	ds_read_b64_tr_b16 v[240:241], v238 offset:48192
	ds_read_b64_tr_b16 v[242:243], v238 offset:49728
	ds_read_b128 v[170:173], v235 offset:6656
	ds_read_b128 v[174:177], v235 offset:6688
	ds_read_b128 v[178:181], v235 offset:6720
	ds_read_b128 v[182:185], v235 offset:6752
	ds_read_b128 v[186:189], v235 offset:6784
	ds_read_b128 v[190:193], v235 offset:6816
	global_load_dwordx4 v[106:109], v212, s[2:3]
	global_load_dwordx4 v[102:105], v210, s[6:7]
	v_add_u32_e32 v212, 0x3000, v212
	v_add_u32_e32 v210, 0x2000, v210
	v_max3_f32 v0, v34, v35, v36
	v_max3_f32 v216, v66, v67, v68
	v_max3_f32 v0, v0, v37, v38
	v_max3_f32 v216, v216, v69, v70
	v_max3_f32 v0, v0, v39, v40
	v_max3_f32 v216, v216, v71, v72
	v_max3_f32 v0, v0, v41, v42
	v_max3_f32 v216, v216, v73, v74
	v_max3_f32 v0, v0, v43, v44
	v_max3_f32 v216, v216, v75, v76
	v_max3_f32 v0, v0, v45, v46
	v_max3_f32 v216, v216, v77, v78
	v_max3_f32 v0, v0, v47, v48
	v_max3_f32 v216, v216, v79, v80
	v_max3_f32 v0, v0, v49, v81
	v_max_f32_e32 v0, v0, v216
	v_mov_b32_e32 v216, v0
	s_nop 1
	v_permlane32_swap_b32_e32 v0, v216
	v_max_f32_e32 v0, v0, v216
	v_cmp_lt_f32_e32 vcc, s52, v0
	s_cbranch_vccz .Lmla_bT_norescale
; __device__ __forceinline__ void mla_unit(LAS unsigned char* lds, const bf16_t* Q, const bf16_t* K, const bf16_t* V, bf16_t* Y, const float* qgain, const float* ROPE, int b, int h, int qb) {
;     ...
;     if (wid >= 4) __builtin_amdgcn_s_setprio(1);
;     for (int t = 0; t < 64; t += 2) { MLA_STEP(p0, p1, n0, n1, t, ka1, kb1, vv0, ka0, kb0, vv1); MLA_STEP(n0, n1, p0, p1, t + 1, ka0, kb0, vv1, ka1, kb1, vv0); }
	v_max_f32_e32 v0, 0, v0
	v_exp_f32_e64 v217, -v0
	v_add_f32_e32 v237, v237, v0
	v_sub_f32_e32 v34, v34, v0
	v_sub_f32_e32 v66, v66, v0
	v_sub_f32_e32 v35, v35, v0
	v_sub_f32_e32 v67, v67, v0
	v_sub_f32_e32 v36, v36, v0
	v_sub_f32_e32 v68, v68, v0
	v_sub_f32_e32 v37, v37, v0
	v_sub_f32_e32 v69, v69, v0
	v_sub_f32_e32 v38, v38, v0
	v_sub_f32_e32 v70, v70, v0
	v_sub_f32_e32 v39, v39, v0
	v_sub_f32_e32 v71, v71, v0
	v_sub_f32_e32 v40, v40, v0
	v_sub_f32_e32 v72, v72, v0
	v_sub_f32_e32 v41, v41, v0
	v_sub_f32_e32 v73, v73, v0
	v_sub_f32_e32 v42, v42, v0
	v_sub_f32_e32 v74, v74, v0
	v_sub_f32_e32 v43, v43, v0
	v_sub_f32_e32 v75, v75, v0
	v_sub_f32_e32 v44, v44, v0
	v_sub_f32_e32 v76, v76, v0
	v_sub_f32_e32 v45, v45, v0
	v_sub_f32_e32 v77, v77, v0
	v_sub_f32_e32 v46, v46, v0
	v_sub_f32_e32 v78, v78, v0
	v_sub_f32_e32 v47, v47, v0
	v_sub_f32_e32 v79, v79, v0
	v_sub_f32_e32 v48, v48, v0
	v_sub_f32_e32 v80, v80, v0
	v_sub_f32_e32 v49, v49, v0
	v_sub_f32_e32 v81, v81, v0
	v_mul_f32_e32 v2, v2, v217
	v_mul_f32_e32 v3, v3, v217
	v_mul_f32_e32 v4, v4, v217
	v_mul_f32_e32 v5, v5, v217
	v_mul_f32_e32 v6, v6, v217
	v_mul_f32_e32 v7, v7, v217
	v_mul_f32_e32 v8, v8, v217
	v_mul_f32_e32 v9, v9, v217
	v_mul_f32_e32 v10, v10, v217
	v_mul_f32_e32 v11, v11, v217
	v_mul_f32_e32 v12, v12, v217
	v_mul_f32_e32 v13, v13, v217
	v_mul_f32_e32 v14, v14, v217
	v_mul_f32_e32 v15, v15, v217
	v_mul_f32_e32 v16, v16, v217
	v_mul_f32_e32 v17, v17, v217
	v_mul_f32_e32 v18, v18, v217
	v_mul_f32_e32 v19, v19, v217
	v_mul_f32_e32 v20, v20, v217
	v_mul_f32_e32 v21, v21, v217
	v_mul_f32_e32 v22, v22, v217
	v_mul_f32_e32 v23, v23, v217
	v_mul_f32_e32 v24, v24, v217
	v_mul_f32_e32 v25, v25, v217
	v_mul_f32_e32 v26, v26, v217
	v_mul_f32_e32 v27, v27, v217
	v_mul_f32_e32 v28, v28, v217
	v_mul_f32_e32 v29, v29, v217
	v_mul_f32_e32 v30, v30, v217
	v_mul_f32_e32 v31, v31, v217
	v_mul_f32_e32 v32, v32, v217
	v_mul_f32_e32 v33, v33, v217
	v_mul_f32_e32 v239, v239, v217
	v_xor_b32_e32 v50, 0x80000000, v237
	v_mov_b32_e32 v51, v50
	v_mov_b32_e32 v52, v50
	v_mov_b32_e32 v53, v50
	v_mov_b32_e32 v54, v50
	v_mov_b32_e32 v55, v50
	v_mov_b32_e32 v56, v50
	v_mov_b32_e32 v57, v50
	v_mov_b32_e32 v58, v50
	v_mov_b32_e32 v59, v50
	v_mov_b32_e32 v60, v50
	v_mov_b32_e32 v61, v50
	v_mov_b32_e32 v62, v50
	v_mov_b32_e32 v63, v50
	v_mov_b32_e32 v64, v50
	v_mov_b32_e32 v65, v50
.Lmla_bT_norescale:
	v_exp_f32_e32 v34, v34
	v_exp_f32_e32 v66, v66
	v_exp_f32_e32 v35, v35
	v_exp_f32_e32 v67, v67
	v_exp_f32_e32 v36, v36
	v_exp_f32_e32 v68, v68
	v_exp_f32_e32 v37, v37
	v_exp_f32_e32 v69, v69
	v_exp_f32_e32 v38, v38
	v_exp_f32_e32 v70, v70
	v_exp_f32_e32 v39, v39
	v_exp_f32_e32 v71, v71
	v_exp_f32_e32 v40, v40
	v_exp_f32_e32 v72, v72
	v_exp_f32_e32 v41, v41
	v_exp_f32_e32 v73, v73
	v_exp_f32_e32 v42, v42
	v_exp_f32_e32 v74, v74
	v_exp_f32_e32 v43, v43
	v_exp_f32_e32 v75, v75
	v_exp_f32_e32 v44, v44
	v_exp_f32_e32 v76, v76
	v_exp_f32_e32 v45, v45
	v_exp_f32_e32 v77, v77
	v_exp_f32_e32 v46, v46
	v_exp_f32_e32 v78, v78
	v_exp_f32_e32 v47, v47
	v_exp_f32_e32 v79, v79
	v_exp_f32_e32 v48, v48
	v_exp_f32_e32 v80, v80
	v_exp_f32_e32 v49, v49
	v_exp_f32_e32 v81, v81
	v_pk_add_f32 v[218:219], v[34:35], v[36:37]
	v_pk_add_f32 v[244:245], v[66:67], v[68:69]
	v_pk_add_f32 v[218:219], v[218:219], v[38:39]
	v_pk_add_f32 v[244:245], v[244:245], v[70:71]
	v_pk_add_f32 v[218:219], v[218:219], v[40:41]
	v_pk_add_f32 v[244:245], v[244:245], v[72:73]
	v_pk_add_f32 v[218:219], v[218:219], v[42:43]
	v_pk_add_f32 v[244:245], v[244:245], v[74:75]
	v_pk_add_f32 v[218:219], v[218:219], v[44:45]
	v_pk_add_f32 v[244:245], v[244:245], v[76:77]
	v_pk_add_f32 v[218:219], v[218:219], v[46:47]
	v_pk_add_f32 v[244:245], v[244:245], v[78:79]
	v_pk_add_f32 v[218:219], v[218:219], v[48:49]
	v_pk_add_f32 v[244:245], v[244:245], v[80:81]
	v_pk_add_f32 v[218:219], v[218:219], v[244:245]
	v_add_f32_e32 v218, v218, v219
	v_add_f32_e32 v239, v239, v218
	v_cvt_pk_bf16_f32 v34, v34, v35
	v_cvt_pk_bf16_f32 v35, v36, v37
	v_cvt_pk_bf16_f32 v36, v38, v39
	v_cvt_pk_bf16_f32 v37, v40, v41
	v_cvt_pk_bf16_f32 v38, v42, v43
	v_cvt_pk_bf16_f32 v39, v44, v45
	v_cvt_pk_bf16_f32 v40, v46, v47
	v_cvt_pk_bf16_f32 v41, v48, v49
	v_cvt_pk_bf16_f32 v42, v66, v67
	v_cvt_pk_bf16_f32 v43, v68, v69
	v_cvt_pk_bf16_f32 v44, v70, v71
	v_cvt_pk_bf16_f32 v45, v72, v73
	v_cvt_pk_bf16_f32 v46, v74, v75
	v_cvt_pk_bf16_f32 v47, v76, v77
	v_cvt_pk_bf16_f32 v48, v78, v79
	v_cvt_pk_bf16_f32 v49, v80, v81
	s_waitcnt lgkmcnt(0)
	s_barrier
	v_mfma_f32_32x32x16_bf16 v[66:81], v[146:149], v[114:117], v[50:65]
	v_mfma_f32_32x32x16_bf16 v[66:81], v[150:153], v[118:121], v[66:81]
	v_mfma_f32_32x32x16_bf16 v[66:81], v[154:157], v[122:125], v[66:81]
	v_mfma_f32_32x32x16_bf16 v[66:81], v[158:161], v[126:129], v[66:81]
	v_mfma_f32_32x32x16_bf16 v[66:81], v[162:165], v[130:133], v[66:81]
	v_mfma_f32_32x32x16_bf16 v[66:81], v[166:169], v[134:137], v[66:81]
	v_mfma_f32_32x32x16_bf16 v[18:33], v[82:85], v[34:37], v[18:33]
	v_mfma_f32_32x32x16_bf16 v[2:17], v[86:89], v[34:37], v[2:17]
	v_mfma_f32_32x32x16_bf16 v[18:33], v[90:93], v[38:41], v[18:33]
	v_mfma_f32_32x32x16_bf16 v[2:17], v[94:97], v[38:41], v[2:17]
	v_mfma_f32_32x32x16_bf16 v[18:33], v[194:197], v[42:45], v[18:33]
	v_mfma_f32_32x32x16_bf16 v[2:17], v[198:201], v[42:45], v[2:17]
	v_mfma_f32_32x32x16_bf16 v[18:33], v[202:205], v[46:49], v[18:33]
	v_mfma_f32_32x32x16_bf16 v[2:17], v[240:243], v[46:49], v[2:17]
	v_mfma_f32_32x32x16_bf16 v[34:49], v[170:173], v[114:117], v[50:65]
	v_mfma_f32_32x32x16_bf16 v[34:49], v[174:177], v[118:121], v[34:49]
	v_mfma_f32_32x32x16_bf16 v[34:49], v[178:181], v[122:125], v[34:49]
	v_mfma_f32_32x32x16_bf16 v[34:49], v[182:185], v[126:129], v[34:49]
	v_mfma_f32_32x32x16_bf16 v[34:49], v[186:189], v[130:133], v[34:49]
	v_mfma_f32_32x32x16_bf16 v[34:49], v[190:193], v[134:137], v[34:49]
	s_waitcnt lgkmcnt(0)
	s_barrier
	s_add_i32 s10, s10, 2
	s_cmp_lt_u32 s10, 64
	s_cbranch_scc1 .Lmla_loop_T
	s_branch .LBB0_387
.Lmla_loop_L:
	ds_read_b128 v[146:149], v235 offset:13312
	ds_read_b128 v[150:153], v235 offset:13344
	ds_read_b128 v[154:157], v235 offset:13376
	ds_read_b128 v[158:161], v235 offset:13408
	ds_read_b128 v[162:165], v235 offset:13440
	ds_read_b128 v[166:169], v235 offset:13472
	ds_read_b64_tr_b16 v[82:83], v238 offset:26624
	ds_read_b64_tr_b16 v[84:85], v238 offset:28160
	ds_read_b64_tr_b16 v[86:87], v238 offset:26688
	ds_read_b64_tr_b16 v[88:89], v238 offset:28224
	ds_read_b64_tr_b16 v[90:91], v238 offset:29696
	ds_read_b64_tr_b16 v[92:93], v238 offset:31232
	ds_read_b64_tr_b16 v[94:95], v238 offset:29760
	ds_read_b64_tr_b16 v[96:97], v238 offset:31296
	ds_read_b64_tr_b16 v[194:195], v238 offset:32768
	ds_read_b64_tr_b16 v[196:197], v238 offset:34304
	ds_read_b64_tr_b16 v[198:199], v238 offset:32832
	ds_read_b64_tr_b16 v[200:201], v238 offset:34368
	ds_read_b64_tr_b16 v[202:203], v238 offset:35840
	ds_read_b64_tr_b16 v[204:205], v238 offset:37376
	ds_read_b64_tr_b16 v[240:241], v238 offset:35904
	ds_read_b64_tr_b16 v[242:243], v238 offset:37440
	ds_read_b128 v[170:173], v235 offset:19968
	ds_read_b128 v[174:177], v235 offset:20000
	ds_read_b128 v[178:181], v235 offset:20032
	ds_read_b128 v[182:185], v235 offset:20064
	ds_read_b128 v[186:189], v235 offset:20096
	ds_read_b128 v[190:193], v235 offset:20128
	v_max3_f32 v0, v66, v67, v68
	v_max3_f32 v216, v34, v35, v36
	v_max3_f32 v0, v0, v69, v70
	v_max3_f32 v216, v216, v37, v38
	v_max3_f32 v0, v0, v71, v72
	v_max3_f32 v216, v216, v39, v40
	v_max3_f32 v0, v0, v73, v74
	v_max3_f32 v216, v216, v41, v42
	v_max3_f32 v0, v0, v75, v76
	v_max3_f32 v216, v216, v43, v44
	v_max3_f32 v0, v0, v77, v78
	v_max3_f32 v216, v216, v45, v46
	v_max3_f32 v0, v0, v79, v80
	v_max3_f32 v216, v216, v47, v48
	v_max3_f32 v0, v0, v81, v49
	v_max_f32_e32 v0, v0, v216
	v_mov_b32_e32 v216, v0
	s_nop 1
	v_permlane32_swap_b32_e32 v0, v216
	v_max_f32_e32 v0, v0, v216
	v_cmp_lt_f32_e32 vcc, s52, v0
	s_cbranch_vccz .Lmla_aL_norescale
	v_max_f32_e32 v0, 0, v0
	v_exp_f32_e64 v217, -v0
	v_add_f32_e32 v237, v237, v0
	v_sub_f32_e32 v66, v66, v0
	v_sub_f32_e32 v34, v34, v0
	v_sub_f32_e32 v67, v67, v0
	v_sub_f32_e32 v35, v35, v0
	v_sub_f32_e32 v68, v68, v0
	v_sub_f32_e32 v36, v36, v0
	v_sub_f32_e32 v69, v69, v0
	v_sub_f32_e32 v37, v37, v0
	v_sub_f32_e32 v70, v70, v0
	v_sub_f32_e32 v38, v38, v0
	v_sub_f32_e32 v71, v71, v0
	v_sub_f32_e32 v39, v39, v0
	v_sub_f32_e32 v72, v72, v0
	v_sub_f32_e32 v40, v40, v0
	v_sub_f32_e32 v73, v73, v0
	v_sub_f32_e32 v41, v41, v0
	v_sub_f32_e32 v74, v74, v0
	v_sub_f32_e32 v42, v42, v0
	v_sub_f32_e32 v75, v75, v0
	v_sub_f32_e32 v43, v43, v0
	v_sub_f32_e32 v76, v76, v0
	v_sub_f32_e32 v44, v44, v0
	v_sub_f32_e32 v77, v77, v0
	v_sub_f32_e32 v45, v45, v0
	v_sub_f32_e32 v78, v78, v0
	v_sub_f32_e32 v46, v46, v0
	v_sub_f32_e32 v79, v79, v0
	v_sub_f32_e32 v47, v47, v0
	v_sub_f32_e32 v80, v80, v0
	v_sub_f32_e32 v48, v48, v0
	v_sub_f32_e32 v81, v81, v0
	v_sub_f32_e32 v49, v49, v0
	v_mul_f32_e32 v2, v2, v217
	v_mul_f32_e32 v3, v3, v217
	v_mul_f32_e32 v4, v4, v217
	v_mul_f32_e32 v5, v5, v217
	v_mul_f32_e32 v6, v6, v217
	v_mul_f32_e32 v7, v7, v217
	v_mul_f32_e32 v8, v8, v217
	v_mul_f32_e32 v9, v9, v217
	v_mul_f32_e32 v10, v10, v217
	v_mul_f32_e32 v11, v11, v217
	v_mul_f32_e32 v12, v12, v217
	v_mul_f32_e32 v13, v13, v217
	v_mul_f32_e32 v14, v14, v217
	v_mul_f32_e32 v15, v15, v217
	v_mul_f32_e32 v16, v16, v217
	v_mul_f32_e32 v17, v17, v217
	v_mul_f32_e32 v18, v18, v217
	v_mul_f32_e32 v19, v19, v217
	v_mul_f32_e32 v20, v20, v217
	v_mul_f32_e32 v21, v21, v217
	v_mul_f32_e32 v22, v22, v217
	v_mul_f32_e32 v23, v23, v217
	v_mul_f32_e32 v24, v24, v217
	v_mul_f32_e32 v25, v25, v217
	v_mul_f32_e32 v26, v26, v217
	v_mul_f32_e32 v27, v27, v217
	v_mul_f32_e32 v28, v28, v217
	v_mul_f32_e32 v29, v29, v217
	v_mul_f32_e32 v30, v30, v217
	v_mul_f32_e32 v31, v31, v217
	v_mul_f32_e32 v32, v32, v217
	v_mul_f32_e32 v33, v33, v217
	v_mul_f32_e32 v239, v239, v217
	v_xor_b32_e32 v50, 0x80000000, v237
	v_mov_b32_e32 v51, v50
	v_mov_b32_e32 v52, v50
	v_mov_b32_e32 v53, v50
	v_mov_b32_e32 v54, v50
	v_mov_b32_e32 v55, v50
	v_mov_b32_e32 v56, v50
	v_mov_b32_e32 v57, v50
	v_mov_b32_e32 v58, v50
	v_mov_b32_e32 v59, v50
	v_mov_b32_e32 v60, v50
	v_mov_b32_e32 v61, v50
	v_mov_b32_e32 v62, v50
	v_mov_b32_e32 v63, v50
	v_mov_b32_e32 v64, v50
	v_mov_b32_e32 v65, v50
.Lmla_aL_norescale:
	v_exp_f32_e32 v66, v66
	v_exp_f32_e32 v34, v34
	v_exp_f32_e32 v67, v67
	v_exp_f32_e32 v35, v35
	v_exp_f32_e32 v68, v68
	v_exp_f32_e32 v36, v36
	v_exp_f32_e32 v69, v69
	v_exp_f32_e32 v37, v37
	v_exp_f32_e32 v70, v70
	v_exp_f32_e32 v38, v38
	v_exp_f32_e32 v71, v71
	v_exp_f32_e32 v39, v39
	v_exp_f32_e32 v72, v72
	v_exp_f32_e32 v40, v40
	v_exp_f32_e32 v73, v73
	v_exp_f32_e32 v41, v41
	v_exp_f32_e32 v74, v74
	v_exp_f32_e32 v42, v42
	v_exp_f32_e32 v75, v75
	v_exp_f32_e32 v43, v43
	v_exp_f32_e32 v76, v76
	v_exp_f32_e32 v44, v44
	v_exp_f32_e32 v77, v77
	v_exp_f32_e32 v45, v45
	v_exp_f32_e32 v78, v78
	v_exp_f32_e32 v46, v46
	v_exp_f32_e32 v79, v79
	v_exp_f32_e32 v47, v47
	v_exp_f32_e32 v80, v80
	v_exp_f32_e32 v48, v48
	v_exp_f32_e32 v81, v81
	v_exp_f32_e32 v49, v49
	v_pk_add_f32 v[218:219], v[66:67], v[68:69]
	v_pk_add_f32 v[244:245], v[34:35], v[36:37]
	v_pk_add_f32 v[218:219], v[218:219], v[70:71]
	v_pk_add_f32 v[244:245], v[244:245], v[38:39]
	v_pk_add_f32 v[218:219], v[218:219], v[72:73]
	v_pk_add_f32 v[244:245], v[244:245], v[40:41]
	v_pk_add_f32 v[218:219], v[218:219], v[74:75]
	v_pk_add_f32 v[244:245], v[244:245], v[42:43]
	v_pk_add_f32 v[218:219], v[218:219], v[76:77]
	v_pk_add_f32 v[244:245], v[244:245], v[44:45]
	v_pk_add_f32 v[218:219], v[218:219], v[78:79]
	v_pk_add_f32 v[244:245], v[244:245], v[46:47]
	v_pk_add_f32 v[218:219], v[218:219], v[80:81]
	v_pk_add_f32 v[244:245], v[244:245], v[48:49]
	v_pk_add_f32 v[218:219], v[218:219], v[244:245]
	v_add_f32_e32 v218, v218, v219
	v_add_f32_e32 v239, v239, v218
	v_cvt_pk_bf16_f32 v66, v66, v67
	v_cvt_pk_bf16_f32 v67, v68, v69
	v_cvt_pk_bf16_f32 v68, v70, v71
	v_cvt_pk_bf16_f32 v69, v72, v73
	v_cvt_pk_bf16_f32 v70, v74, v75
	v_cvt_pk_bf16_f32 v71, v76, v77
	v_cvt_pk_bf16_f32 v72, v78, v79
	v_cvt_pk_bf16_f32 v73, v80, v81
	v_cvt_pk_bf16_f32 v74, v34, v35
	v_cvt_pk_bf16_f32 v75, v36, v37
	v_cvt_pk_bf16_f32 v76, v38, v39
	v_cvt_pk_bf16_f32 v77, v40, v41
	v_cvt_pk_bf16_f32 v78, v42, v43
	v_cvt_pk_bf16_f32 v79, v44, v45
	v_cvt_pk_bf16_f32 v80, v46, v47
	v_cvt_pk_bf16_f32 v81, v48, v49
	s_waitcnt lgkmcnt(0)
	s_barrier
	s_waitcnt vmcnt(3)
	ds_write_b128 v223, v[138:141]
	ds_write_b128 v234, v[98:101]
	ds_write_b128 v233, v[142:145] offset:38912
	v_mfma_f32_32x32x16_bf16 v[34:49], v[146:149], v[114:117], v[50:65]
	v_mfma_f32_32x32x16_bf16 v[34:49], v[150:153], v[118:121], v[34:49]
	v_mfma_f32_32x32x16_bf16 v[34:49], v[154:157], v[122:125], v[34:49]
	v_mfma_f32_32x32x16_bf16 v[34:49], v[158:161], v[126:129], v[34:49]
	v_mfma_f32_32x32x16_bf16 v[34:49], v[162:165], v[130:133], v[34:49]
	v_mfma_f32_32x32x16_bf16 v[34:49], v[166:169], v[134:137], v[34:49]
	global_load_dwordx4 v[138:141], v212, s[2:3]
	global_load_dwordx4 v[98:101], v214, s[2:3]
	global_load_dwordx4 v[142:145], v210, s[6:7]
	v_add_u32_e32 v212, 0x3000, v212
	v_add_u32_e32 v214, 0x3000, v214
	v_add_u32_e32 v210, 0x2000, v210
	v_mfma_f32_32x32x16_bf16 v[18:33], v[82:85], v[66:69], v[18:33]
	v_mfma_f32_32x32x16_bf16 v[2:17], v[86:89], v[66:69], v[2:17]
	v_mfma_f32_32x32x16_bf16 v[18:33], v[90:93], v[70:73], v[18:33]
	v_mfma_f32_32x32x16_bf16 v[2:17], v[94:97], v[70:73], v[2:17]
	v_mfma_f32_32x32x16_bf16 v[18:33], v[194:197], v[74:77], v[18:33]
	v_mfma_f32_32x32x16_bf16 v[2:17], v[198:201], v[74:77], v[2:17]
	v_mfma_f32_32x32x16_bf16 v[18:33], v[202:205], v[78:81], v[18:33]
	v_mfma_f32_32x32x16_bf16 v[2:17], v[240:243], v[78:81], v[2:17]
	v_mfma_f32_32x32x16_bf16 v[66:81], v[170:173], v[114:117], v[50:65]
	v_mfma_f32_32x32x16_bf16 v[66:81], v[174:177], v[118:121], v[66:81]
	v_mfma_f32_32x32x16_bf16 v[66:81], v[178:181], v[122:125], v[66:81]
	v_mfma_f32_32x32x16_bf16 v[66:81], v[182:185], v[126:129], v[66:81]
	v_mfma_f32_32x32x16_bf16 v[66:81], v[186:189], v[130:133], v[66:81]
	v_mfma_f32_32x32x16_bf16 v[66:81], v[190:193], v[134:137], v[66:81]
	s_waitcnt lgkmcnt(0)
	s_barrier
	ds_read_b128 v[146:149], v235 offset:0
	ds_read_b128 v[150:153], v235 offset:32
	ds_read_b128 v[154:157], v235 offset:64
	ds_read_b128 v[158:161], v235 offset:96
	ds_read_b128 v[162:165], v235 offset:128
	ds_read_b128 v[166:169], v235 offset:160
	ds_read_b64_tr_b16 v[82:83], v238 offset:38912
	ds_read_b64_tr_b16 v[84:85], v238 offset:40448
	ds_read_b64_tr_b16 v[86:87], v238 offset:38976
	ds_read_b64_tr_b16 v[88:89], v238 offset:40512
	ds_read_b64_tr_b16 v[90:91], v238 offset:41984
	ds_read_b64_tr_b16 v[92:93], v238 offset:43520
	ds_read_b64_tr_b16 v[94:95], v238 offset:42048
	ds_read_b64_tr_b16 v[96:97], v238 offset:43584
	ds_read_b64_tr_b16 v[194:195], v238 offset:45056
	ds_read_b64_tr_b16 v[196:197], v238 offset:46592
	ds_read_b64_tr_b16 v[198:199], v238 offset:45120
	ds_read_b64_tr_b16 v[200:201], v238 offset:46656
	ds_read_b64_tr_b16 v[202:203], v238 offset:48128
	ds_read_b64_tr_b16 v[204:205], v238 offset:49664
	ds_read_b64_tr_b16 v[240:241], v238 offset:48192
	ds_read_b64_tr_b16 v[242:243], v238 offset:49728
	ds_read_b128 v[170:173], v235 offset:6656
	ds_read_b128 v[174:177], v235 offset:6688
	ds_read_b128 v[178:181], v235 offset:6720
	ds_read_b128 v[182:185], v235 offset:6752
	ds_read_b128 v[186:189], v235 offset:6784
	ds_read_b128 v[190:193], v235 offset:6816
	v_max3_f32 v0, v34, v35, v36
	v_max3_f32 v216, v66, v67, v68
	v_max3_f32 v0, v0, v37, v38
	v_max3_f32 v216, v216, v69, v70
	v_max3_f32 v0, v0, v39, v40
	v_max3_f32 v216, v216, v71, v72
	v_max3_f32 v0, v0, v41, v42
	v_max3_f32 v216, v216, v73, v74
	v_max3_f32 v0, v0, v43, v44
	v_max3_f32 v216, v216, v75, v76
	v_max3_f32 v0, v0, v45, v46
	v_max3_f32 v216, v216, v77, v78
	v_max3_f32 v0, v0, v47, v48
	v_max3_f32 v216, v216, v79, v80
	v_max3_f32 v0, v0, v49, v81
	v_max_f32_e32 v0, v0, v216
	v_mov_b32_e32 v216, v0
	s_nop 1
	v_permlane32_swap_b32_e32 v0, v216
	v_max_f32_e32 v0, v0, v216
	v_cmp_lt_f32_e32 vcc, s52, v0
	s_cbranch_vccz .Lmla_bL_norescale
; __device__ __forceinline__ void mla_unit(LAS unsigned char* lds, const bf16_t* Q, const bf16_t* K, const bf16_t* V, bf16_t* Y, const float* qgain, const float* ROPE, int b, int h, int qb) {
;     ...
;     if (wid >= 4) __builtin_amdgcn_s_setprio(1);
;     for (int t = 0; t < 64; t += 2) { MLA_STEP(p0, p1, n0, n1, t, ka1, kb1, vv0, ka0, kb0, vv1); MLA_STEP(n0, n1, p0, p1, t + 1, ka0, kb0, vv1, ka1, kb1, vv0); }
	v_max_f32_e32 v0, 0, v0
	v_exp_f32_e64 v217, -v0
	v_add_f32_e32 v237, v237, v0
	v_sub_f32_e32 v34, v34, v0
	v_sub_f32_e32 v66, v66, v0
	v_sub_f32_e32 v35, v35, v0
	v_sub_f32_e32 v67, v67, v0
	v_sub_f32_e32 v36, v36, v0
	v_sub_f32_e32 v68, v68, v0
	v_sub_f32_e32 v37, v37, v0
	v_sub_f32_e32 v69, v69, v0
	v_sub_f32_e32 v38, v38, v0
	v_sub_f32_e32 v70, v70, v0
	v_sub_f32_e32 v39, v39, v0
	v_sub_f32_e32 v71, v71, v0
	v_sub_f32_e32 v40, v40, v0
	v_sub_f32_e32 v72, v72, v0
	v_sub_f32_e32 v41, v41, v0
	v_sub_f32_e32 v73, v73, v0
	v_sub_f32_e32 v42, v42, v0
	v_sub_f32_e32 v74, v74, v0
	v_sub_f32_e32 v43, v43, v0
	v_sub_f32_e32 v75, v75, v0
	v_sub_f32_e32 v44, v44, v0
	v_sub_f32_e32 v76, v76, v0
	v_sub_f32_e32 v45, v45, v0
	v_sub_f32_e32 v77, v77, v0
	v_sub_f32_e32 v46, v46, v0
	v_sub_f32_e32 v78, v78, v0
	v_sub_f32_e32 v47, v47, v0
	v_sub_f32_e32 v79, v79, v0
	v_sub_f32_e32 v48, v48, v0
	v_sub_f32_e32 v80, v80, v0
	v_sub_f32_e32 v49, v49, v0
	v_sub_f32_e32 v81, v81, v0
	v_mul_f32_e32 v2, v2, v217
	v_mul_f32_e32 v3, v3, v217
	v_mul_f32_e32 v4, v4, v217
	v_mul_f32_e32 v5, v5, v217
	v_mul_f32_e32 v6, v6, v217
	v_mul_f32_e32 v7, v7, v217
	v_mul_f32_e32 v8, v8, v217
	v_mul_f32_e32 v9, v9, v217
	v_mul_f32_e32 v10, v10, v217
	v_mul_f32_e32 v11, v11, v217
	v_mul_f32_e32 v12, v12, v217
	v_mul_f32_e32 v13, v13, v217
	v_mul_f32_e32 v14, v14, v217
	v_mul_f32_e32 v15, v15, v217
	v_mul_f32_e32 v16, v16, v217
	v_mul_f32_e32 v17, v17, v217
	v_mul_f32_e32 v18, v18, v217
	v_mul_f32_e32 v19, v19, v217
	v_mul_f32_e32 v20, v20, v217
	v_mul_f32_e32 v21, v21, v217
	v_mul_f32_e32 v22, v22, v217
	v_mul_f32_e32 v23, v23, v217
	v_mul_f32_e32 v24, v24, v217
	v_mul_f32_e32 v25, v25, v217
	v_mul_f32_e32 v26, v26, v217
	v_mul_f32_e32 v27, v27, v217
	v_mul_f32_e32 v28, v28, v217
	v_mul_f32_e32 v29, v29, v217
	v_mul_f32_e32 v30, v30, v217
	v_mul_f32_e32 v31, v31, v217
	v_mul_f32_e32 v32, v32, v217
	v_mul_f32_e32 v33, v33, v217
	v_mul_f32_e32 v239, v239, v217
	v_xor_b32_e32 v50, 0x80000000, v237
	v_mov_b32_e32 v51, v50
	v_mov_b32_e32 v52, v50
	v_mov_b32_e32 v53, v50
	v_mov_b32_e32 v54, v50
	v_mov_b32_e32 v55, v50
	v_mov_b32_e32 v56, v50
	v_mov_b32_e32 v57, v50
	v_mov_b32_e32 v58, v50
	v_mov_b32_e32 v59, v50
	v_mov_b32_e32 v60, v50
	v_mov_b32_e32 v61, v50
	v_mov_b32_e32 v62, v50
	v_mov_b32_e32 v63, v50
	v_mov_b32_e32 v64, v50
	v_mov_b32_e32 v65, v50
.Lmla_bL_norescale:
	v_exp_f32_e32 v34, v34
	v_exp_f32_e32 v66, v66
	v_exp_f32_e32 v35, v35
	v_exp_f32_e32 v67, v67
	v_exp_f32_e32 v36, v36
	v_exp_f32_e32 v68, v68
	v_exp_f32_e32 v37, v37
	v_exp_f32_e32 v69, v69
	v_exp_f32_e32 v38, v38
	v_exp_f32_e32 v70, v70
	v_exp_f32_e32 v39, v39
	v_exp_f32_e32 v71, v71
	v_exp_f32_e32 v40, v40
	v_exp_f32_e32 v72, v72
	v_exp_f32_e32 v41, v41
	v_exp_f32_e32 v73, v73
	v_exp_f32_e32 v42, v42
	v_exp_f32_e32 v74, v74
	v_exp_f32_e32 v43, v43
	v_exp_f32_e32 v75, v75
	v_exp_f32_e32 v44, v44
	v_exp_f32_e32 v76, v76
	v_exp_f32_e32 v45, v45
	v_exp_f32_e32 v77, v77
	v_exp_f32_e32 v46, v46
	v_exp_f32_e32 v78, v78
	v_exp_f32_e32 v47, v47
	v_exp_f32_e32 v79, v79
	v_exp_f32_e32 v48, v48
	v_exp_f32_e32 v80, v80
	v_exp_f32_e32 v49, v49
	v_exp_f32_e32 v81, v81
	v_pk_add_f32 v[218:219], v[34:35], v[36:37]
	v_pk_add_f32 v[244:245], v[66:67], v[68:69]
	v_pk_add_f32 v[218:219], v[218:219], v[38:39]
	v_pk_add_f32 v[244:245], v[244:245], v[70:71]
	v_pk_add_f32 v[218:219], v[218:219], v[40:41]
	v_pk_add_f32 v[244:245], v[244:245], v[72:73]
	v_pk_add_f32 v[218:219], v[218:219], v[42:43]
	v_pk_add_f32 v[244:245], v[244:245], v[74:75]
	v_pk_add_f32 v[218:219], v[218:219], v[44:45]
	v_pk_add_f32 v[244:245], v[244:245], v[76:77]
	v_pk_add_f32 v[218:219], v[218:219], v[46:47]
	v_pk_add_f32 v[244:245], v[244:245], v[78:79]
	v_pk_add_f32 v[218:219], v[218:219], v[48:49]
	v_pk_add_f32 v[244:245], v[244:245], v[80:81]
	v_pk_add_f32 v[218:219], v[218:219], v[244:245]
	v_add_f32_e32 v218, v218, v219
	v_add_f32_e32 v239, v239, v218
	v_cvt_pk_bf16_f32 v34, v34, v35
	v_cvt_pk_bf16_f32 v35, v36, v37
	v_cvt_pk_bf16_f32 v36, v38, v39
	v_cvt_pk_bf16_f32 v37, v40, v41
	v_cvt_pk_bf16_f32 v38, v42, v43
	v_cvt_pk_bf16_f32 v39, v44, v45
	v_cvt_pk_bf16_f32 v40, v46, v47
	v_cvt_pk_bf16_f32 v41, v48, v49
	v_cvt_pk_bf16_f32 v42, v66, v67
	v_cvt_pk_bf16_f32 v43, v68, v69
	v_cvt_pk_bf16_f32 v44, v70, v71
	v_cvt_pk_bf16_f32 v45, v72, v73
	v_cvt_pk_bf16_f32 v46, v74, v75
	v_cvt_pk_bf16_f32 v47, v76, v77
	v_cvt_pk_bf16_f32 v48, v78, v79
	v_cvt_pk_bf16_f32 v49, v80, v81
	s_waitcnt lgkmcnt(0)
	s_barrier
	s_waitcnt vmcnt(3)
	ds_write_b128 v223, v[106:109] offset:13312
	ds_write_b128 v234, v[110:113] offset:13312
	ds_write_b128 v233, v[102:105] offset:26624
	v_mfma_f32_32x32x16_bf16 v[66:81], v[146:149], v[114:117], v[50:65]
	v_mfma_f32_32x32x16_bf16 v[66:81], v[150:153], v[118:121], v[66:81]
	v_mfma_f32_32x32x16_bf16 v[66:81], v[154:157], v[122:125], v[66:81]
	v_mfma_f32_32x32x16_bf16 v[66:81], v[158:161], v[126:129], v[66:81]
	v_mfma_f32_32x32x16_bf16 v[66:81], v[162:165], v[130:133], v[66:81]
	v_mfma_f32_32x32x16_bf16 v[66:81], v[166:169], v[134:137], v[66:81]
	global_load_dwordx4 v[106:109], v212, s[2:3]
	global_load_dwordx4 v[110:113], v214, s[2:3]
	global_load_dwordx4 v[102:105], v210, s[6:7]
	v_add_u32_e32 v212, 0x3000, v212
	v_add_u32_e32 v214, 0x3000, v214
	v_add_u32_e32 v210, 0x2000, v210
	v_mfma_f32_32x32x16_bf16 v[18:33], v[82:85], v[34:37], v[18:33]
	v_mfma_f32_32x32x16_bf16 v[2:17], v[86:89], v[34:37], v[2:17]
	v_mfma_f32_32x32x16_bf16 v[18:33], v[90:93], v[38:41], v[18:33]
	v_mfma_f32_32x32x16_bf16 v[2:17], v[94:97], v[38:41], v[2:17]
	v_mfma_f32_32x32x16_bf16 v[18:33], v[194:197], v[42:45], v[18:33]
	v_mfma_f32_32x32x16_bf16 v[2:17], v[198:201], v[42:45], v[2:17]
	v_mfma_f32_32x32x16_bf16 v[18:33], v[202:205], v[46:49], v[18:33]
	v_mfma_f32_32x32x16_bf16 v[2:17], v[240:243], v[46:49], v[2:17]
	v_mfma_f32_32x32x16_bf16 v[34:49], v[170:173], v[114:117], v[50:65]
	v_mfma_f32_32x32x16_bf16 v[34:49], v[174:177], v[118:121], v[34:49]
	v_mfma_f32_32x32x16_bf16 v[34:49], v[178:181], v[122:125], v[34:49]
	v_mfma_f32_32x32x16_bf16 v[34:49], v[182:185], v[126:129], v[34:49]
	v_mfma_f32_32x32x16_bf16 v[34:49], v[186:189], v[130:133], v[34:49]
	v_mfma_f32_32x32x16_bf16 v[34:49], v[190:193], v[134:137], v[34:49]
	s_waitcnt lgkmcnt(0)
	s_barrier
	s_add_i32 s10, s10, 2
	s_cmp_lt_u32 s10, 64
	s_cbranch_scc1 .Lmla_loop_L
	s_branch .LBB0_387
